# scan PV chains skip the k-slices of P that are exact zeros by causality (per 32-row block, by unit direction): 12 fewer MFMA + 36 fewer LDS reads per wave per step
# speedup vs baseline: 1.0009x; 1.0009x over previous
.LBB0_508:
	v_lshrrev_b32_e32 v66, 3, v140
	v_bfe_u32 v67, v140, 1, 1
	v_lshlrev_b32_e32 v68, 3, v140
	v_and_or_b32 v66, v66, 2, v67
	v_or_b32_e32 v67, v160, v99
	v_and_b32_e32 v68, 8, v68
	v_lshl_or_b32 v163, v67, 8, v68
	v_lshlrev_b32_e32 v67, 2, v99
	v_lshlrev_b32_e32 v68, 1, v130
	v_or_b32_e32 v69, v67, v68
	v_bitop3_b32 v67, v67, v66, v68 bitop3:0x36
	v_add_u32_e32 v136, 0, v72
	v_xor_b32_e32 v68, 16, v132
	v_bitop3_b32 v66, v69, v66, 1 bitop3:0x36
	v_add_u32_e32 v165, v136, v132
	v_add_u32_e32 v166, v136, v68
	v_lshlrev_b32_e32 v161, 4, v67
	v_lshlrev_b32_e32 v162, 4, v66
	ds_read_b64 v[66:67], v165
	ds_read_b64 v[68:69], v166
	v_readlane_b32 s3, v254, 51
	v_xor_b32_e32 v106, 32, v132
	v_xor_b32_e32 v108, 48, v132
	v_add_u32_e32 v133, s3, v163
	s_add_i32 s3, 0, 0x22200
	v_add_u32_e32 v167, v136, v106
	v_add_u32_e32 v168, v136, v108
	v_add_u32_e32 v131, s3, v98
	v_cvt_pk_bf16_f32 v98, v50, v51
	v_cvt_pk_bf16_f32 v99, v52, v53
	v_cvt_pk_bf16_f32 v100, v54, v55
	v_cvt_pk_bf16_f32 v101, v56, v57
	ds_read_b64 v[106:107], v167
	ds_read_b64 v[108:109], v168
	s_waitcnt lgkmcnt(2)
	v_mfma_f32_32x32x16_bf16 v[66:81], v[66:69], v[98:101], 0
	v_xor_b32_e32 v110, 64, v132
	v_xor_b32_e32 v112, 0x50, v132
	v_add_u32_e32 v169, v136, v110
	v_add_u32_e32 v170, v136, v112
	v_cvt_pk_bf16_f32 v102, v58, v59
	v_cvt_pk_bf16_f32 v103, v60, v61
	v_cvt_pk_bf16_f32 v104, v62, v63
	v_cvt_pk_bf16_f32 v105, v64, v65
	ds_read_b64 v[110:111], v169
	ds_read_b64 v[112:113], v170
	s_waitcnt lgkmcnt(2)
	v_mfma_f32_32x32x16_bf16 v[66:81], v[106:109], v[102:105], v[66:81]
	v_xor_b32_e32 v114, 0x60, v132
	v_xor_b32_e32 v116, 0x70, v132
	v_add_u32_e32 v171, v136, v114
	v_add_u32_e32 v172, v136, v116
	v_cvt_pk_bf16_f32 v106, v34, v35
	v_cvt_pk_bf16_f32 v107, v36, v37
	v_cvt_pk_bf16_f32 v108, v38, v39
	v_cvt_pk_bf16_f32 v109, v40, v41
	ds_read_b64 v[114:115], v171
	ds_read_b64 v[116:117], v172
	s_waitcnt lgkmcnt(2)
	v_mfma_f32_32x32x16_bf16 v[66:81], v[110:113], v[106:109], v[66:81]
	v_xor_b32_e32 v118, 0x80, v132
	v_xor_b32_e32 v120, 0x90, v132
	v_add_u32_e32 v173, v136, v118
	v_add_u32_e32 v174, v136, v120
	v_cvt_pk_bf16_f32 v110, v42, v43
	v_cvt_pk_bf16_f32 v111, v44, v45
	v_cvt_pk_bf16_f32 v112, v46, v47
	v_cvt_pk_bf16_f32 v113, v48, v49
	ds_read_b64 v[118:119], v173
	ds_read_b64 v[120:121], v174
	s_waitcnt lgkmcnt(2)
	v_mfma_f32_32x32x16_bf16 v[66:81], v[114:117], v[110:113], v[66:81]
	v_xor_b32_e32 v122, 0xa0, v132
	v_xor_b32_e32 v124, 0xb0, v132
	v_add_u32_e32 v175, v136, v122
	v_add_u32_e32 v176, v136, v124
	v_cvt_pk_bf16_f32 v114, v18, v19
	v_cvt_pk_bf16_f32 v115, v20, v21
	v_cvt_pk_bf16_f32 v116, v22, v23
	v_cvt_pk_bf16_f32 v117, v24, v25
	ds_read_b64 v[122:123], v175
	ds_read_b64 v[124:125], v176
	s_waitcnt lgkmcnt(2)
	v_mfma_f32_32x32x16_bf16 v[66:81], v[118:121], v[114:117], v[66:81]
	v_xor_b32_e32 v126, 0xc0, v132
	v_xor_b32_e32 v128, 0xd0, v132
	v_add_u32_e32 v178, v136, v126
	v_add_u32_e32 v179, v136, v128
	v_cvt_pk_bf16_f32 v118, v26, v27
	v_cvt_pk_bf16_f32 v119, v28, v29
	v_cvt_pk_bf16_f32 v120, v30, v31
	v_cvt_pk_bf16_f32 v121, v32, v33
	ds_read_b64 v[126:127], v178
	ds_read_b64 v[128:129], v179
	s_waitcnt lgkmcnt(2)
	v_mfma_f32_32x32x16_bf16 v[66:81], v[122:125], v[118:121], v[66:81]
	v_xor_b32_e32 v137, 0xe0, v132
	v_xor_b32_e32 v132, 0xf0, v132
	v_add_u32_e32 v180, v136, v137
	v_add_u32_e32 v181, v136, v132
	v_cvt_pk_bf16_f32 v122, v2, v3
	v_cvt_pk_bf16_f32 v123, v4, v5
	v_cvt_pk_bf16_f32 v124, v6, v7
	v_cvt_pk_bf16_f32 v125, v8, v9
	ds_read_b64 v[142:143], v180
	ds_read_b64 v[144:145], v181
	s_waitcnt lgkmcnt(2)
	v_mfma_f32_32x32x16_bf16 v[66:81], v[126:129], v[122:125], v[66:81]
	v_cvt_pk_bf16_f32 v126, v10, v11
	v_cvt_pk_bf16_f32 v127, v12, v13
	v_cvt_pk_bf16_f32 v128, v14, v15
	v_cvt_pk_bf16_f32 v129, v16, v17
	v_lshlrev_b32_e32 v164, 4, v130
	v_add_u32_e32 v132, 0, v164
	v_add_u32_e32 v136, 0x20400, v132
	s_waitcnt lgkmcnt(0)
	v_mfma_f32_32x32x16_bf16 v[66:81], v[142:145], v[126:129], v[66:81]
	ds_read_b128 v[142:145], v136
	ds_read_b128 v[182:185], v136 offset:32
	ds_read_b128 v[186:189], v136 offset:64
	ds_read_b128 v[250:253], v136 offset:96
	v_xor_b32_e32 v135, s48, v161
	v_xor_b32_e32 v134, s48, v162
	v_add_u32_e32 v159, v133, v135
	v_add_u32_e32 v158, v133, v134
	s_and_b64 vcc, exec, s[6:7]
	s_waitcnt lgkmcnt(1)
	s_nop 1
	v_pk_mul_f32 v[74:75], v[74:75], v[186:187]
	v_add_u32_e32 v187, v131, v243
	ds_read_b128 v[134:137], v187
	v_pk_mul_f32 v[68:69], v[68:69], v[144:145]
	v_pk_mul_f32 v[66:67], v[66:67], v[142:143]
	ds_read_b64_tr_b16 v[142:143], v159
	ds_read_b64_tr_b16 v[144:145], v158 offset:1024
	s_waitcnt lgkmcnt(3)
	v_pk_mul_f32 v[80:81], v[80:81], v[252:253]
	v_pk_mul_f32 v[78:79], v[78:79], v[250:251]
	v_pk_mul_f32 v[76:77], v[76:77], v[188:189]
	v_pk_mul_f32 v[72:73], v[72:73], v[184:185]
	v_pk_mul_f32 v[70:71], v[70:71], v[182:183]
	v_add_u32_e32 v188, v131, v245
	v_add_u32_e32 v189, v131, v241
	s_waitcnt lgkmcnt(0)
	v_mfma_f32_32x32x16_bf16 v[66:81], v[134:137], v[142:145], v[66:81]
	ds_read_b64_tr_b16 v[134:135], v159 offset:4096
	ds_read_b64_tr_b16 v[136:137], v158 offset:5120
	ds_read_b128 v[142:145], v188
	v_add_u32_e32 v183, v131, v226
	v_add_u32_e32 v182, v131, v223
	v_add_u32_e32 v184, v131, v225
	v_add_u32_e32 v185, v131, v239
	v_add_u32_e32 v186, v131, v244
	s_waitcnt lgkmcnt(0)
	v_mfma_f32_32x32x16_bf16 v[66:81], v[142:145], v[134:137], v[66:81]
	s_cmp_lg_u32 s4, 0
	s_cbranch_scc1 .Lpv0_done
	ds_read_b64_tr_b16 v[134:135], v159 offset:8192
	ds_read_b64_tr_b16 v[136:137], v158 offset:9216
	ds_read_b128 v[142:145], v189
	s_waitcnt lgkmcnt(0)
	v_mfma_f32_32x32x16_bf16 v[66:81], v[142:145], v[134:137], v[66:81]
	ds_read_b64_tr_b16 v[134:135], v159 offset:12288
	ds_read_b64_tr_b16 v[136:137], v158 offset:13312
	ds_read_b128 v[142:145], v183
	s_waitcnt lgkmcnt(0)
	v_mfma_f32_32x32x16_bf16 v[66:81], v[142:145], v[134:137], v[66:81]
	ds_read_b64_tr_b16 v[134:135], v159 offset:16384
	ds_read_b64_tr_b16 v[136:137], v158 offset:17408
	ds_read_b128 v[142:145], v182
	s_waitcnt lgkmcnt(0)
	v_mfma_f32_32x32x16_bf16 v[66:81], v[142:145], v[134:137], v[66:81]
	ds_read_b64_tr_b16 v[134:135], v159 offset:20480
	ds_read_b64_tr_b16 v[136:137], v158 offset:21504
	ds_read_b128 v[142:145], v184
	s_waitcnt lgkmcnt(0)
	v_mfma_f32_32x32x16_bf16 v[66:81], v[142:145], v[134:137], v[66:81]
	ds_read_b64_tr_b16 v[134:135], v159 offset:24576
	ds_read_b64_tr_b16 v[136:137], v158 offset:25600
	ds_read_b128 v[142:145], v185
	s_waitcnt lgkmcnt(0)
	v_mfma_f32_32x32x16_bf16 v[66:81], v[142:145], v[134:137], v[66:81]
	ds_read_b64_tr_b16 v[134:135], v159 offset:28672
	ds_read_b64_tr_b16 v[136:137], v158 offset:29696
	ds_read_b128 v[142:145], v186
	s_waitcnt lgkmcnt(0)
	v_mfma_f32_32x32x16_bf16 v[66:81], v[142:145], v[134:137], v[66:81]
.Lpv0_done:
	s_cbranch_vccnz .LBB0_510
	v_add_u32_e32 v131, 0x20a00, v132
	ds_read_b128 v[132:135], v131 offset:96
	ds_read_b128 v[142:145], v131 offset:64
	ds_read_b128 v[250:253], v131 offset:32
	ds_read_b128 v[196:199], v131
	s_waitcnt lgkmcnt(3)
	s_nop 4
	v_pk_mul_f32 v[78:79], v[78:79], v[132:133]
	s_waitcnt lgkmcnt(2)
	v_pk_mul_f32 v[74:75], v[74:75], v[142:143]
	s_waitcnt lgkmcnt(1)
	v_pk_mul_f32 v[70:71], v[70:71], v[250:251]
	v_pk_mul_f32 v[80:81], v[80:81], v[134:135]
	v_pk_mul_f32 v[76:77], v[76:77], v[144:145]
	v_pk_mul_f32 v[72:73], v[72:73], v[252:253]
	s_waitcnt lgkmcnt(0)
	v_pk_mul_f32 v[68:69], v[68:69], v[198:199]
	v_pk_mul_f32 v[66:67], v[66:67], v[196:197]

.LBB0_522:
	ds_read_b64 v[66:67], v165 offset:8192
	ds_read_b64 v[68:69], v166 offset:8192
	ds_read_b64 v[130:131], v167 offset:8192
	ds_read_b64 v[132:133], v168 offset:8192
	ds_read_b64 v[134:135], v169 offset:8192
	ds_read_b64 v[136:137], v170 offset:8192
	ds_read_b64 v[196:197], v171 offset:8192
	ds_read_b64 v[198:199], v172 offset:8192
	s_add_i32 s2, 0, 0x20400
	v_add_u32_e32 v219, s2, v164
	s_and_b64 vcc, exec, s[6:7]
	s_waitcnt lgkmcnt(6)
	v_mfma_f32_32x32x16_bf16 v[66:81], v[66:69], v[98:101], 0
	ds_read_b64 v[250:251], v173 offset:8192
	ds_read_b64 v[252:253], v174 offset:8192
	s_waitcnt lgkmcnt(6)
	v_mfma_f32_32x32x16_bf16 v[66:81], v[130:133], v[102:105], v[66:81]
	ds_read_b64 v[130:131], v175 offset:8192
	ds_read_b64 v[132:133], v176 offset:8192
	s_waitcnt lgkmcnt(6)
	v_mfma_f32_32x32x16_bf16 v[66:81], v[134:137], v[106:109], v[66:81]
	ds_read_b64 v[134:135], v178 offset:8192
	ds_read_b64 v[136:137], v179 offset:8192
	s_waitcnt lgkmcnt(6)
	v_mfma_f32_32x32x16_bf16 v[66:81], v[196:199], v[110:113], v[66:81]
	ds_read_b64 v[196:197], v180 offset:8192
	ds_read_b64 v[198:199], v181 offset:8192
	s_waitcnt lgkmcnt(6)
	v_mfma_f32_32x32x16_bf16 v[66:81], v[250:253], v[114:117], v[66:81]
	ds_read_b128 v[250:253], v219 offset:224
	s_waitcnt lgkmcnt(5)
	v_mfma_f32_32x32x16_bf16 v[66:81], v[130:133], v[118:121], v[66:81]
	ds_read_b128 v[130:133], v219 offset:128
	s_waitcnt lgkmcnt(4)
	v_mfma_f32_32x32x16_bf16 v[66:81], v[134:137], v[122:125], v[66:81]
	ds_read_b128 v[134:137], v219 offset:160
	s_waitcnt lgkmcnt(3)
	v_mfma_f32_32x32x16_bf16 v[66:81], v[196:199], v[126:129], v[66:81]
	ds_read_b128 v[196:199], v219 offset:192
	s_waitcnt lgkmcnt(2)
	s_nop 9
	s_cmp_lg_u32 s4, 0
	s_cbranch_scc0 .Lpv1_bwd
	v_pk_mul_f32 v[78:79], v[78:79], v[250:251]
	v_pk_mul_f32 v[80:81], v[80:81], v[252:253]
	v_pk_mul_f32 v[66:67], v[66:67], v[130:131]
	v_pk_mul_f32 v[68:69], v[68:69], v[132:133]
	ds_read_b64_tr_b16 v[130:131], v159
	ds_read_b64_tr_b16 v[132:133], v158 offset:1024
	ds_read_b128 v[250:253], v187 offset:8192
	s_waitcnt lgkmcnt(3)
	v_pk_mul_f32 v[70:71], v[70:71], v[134:135]
	v_pk_mul_f32 v[72:73], v[72:73], v[136:137]
	v_pk_mul_f32 v[74:75], v[74:75], v[196:197]
	v_pk_mul_f32 v[76:77], v[76:77], v[198:199]
	ds_read_b64_tr_b16 v[134:135], v159 offset:4096
	ds_read_b64_tr_b16 v[136:137], v158 offset:5120
	ds_read_b128 v[196:199], v188 offset:8192
	s_waitcnt lgkmcnt(3)
	v_mfma_f32_32x32x16_bf16 v[66:81], v[250:253], v[130:133], v[66:81]
	ds_read_b64_tr_b16 v[130:131], v159 offset:8192
	ds_read_b64_tr_b16 v[132:133], v158 offset:9216
	ds_read_b128 v[250:253], v189 offset:8192
	s_waitcnt lgkmcnt(3)
	v_mfma_f32_32x32x16_bf16 v[66:81], v[196:199], v[134:137], v[66:81]
	ds_read_b64_tr_b16 v[134:135], v159 offset:12288
	ds_read_b64_tr_b16 v[136:137], v158 offset:13312
	ds_read_b128 v[196:199], v183 offset:8192
	s_waitcnt lgkmcnt(3)
	v_mfma_f32_32x32x16_bf16 v[66:81], v[250:253], v[130:133], v[66:81]
	s_waitcnt lgkmcnt(0)
	v_mfma_f32_32x32x16_bf16 v[66:81], v[196:199], v[134:137], v[66:81]
	s_branch .Lpv1_done
.Lpv1_bwd:
	v_pk_mul_f32 v[78:79], v[78:79], v[250:251]
	v_pk_mul_f32 v[80:81], v[80:81], v[252:253]
	v_pk_mul_f32 v[66:67], v[66:67], v[130:131]
	v_pk_mul_f32 v[68:69], v[68:69], v[132:133]
	ds_read_b64_tr_b16 v[130:131], v159 offset:8192
	ds_read_b64_tr_b16 v[132:133], v158 offset:9216
	ds_read_b128 v[250:253], v189 offset:8192
	s_waitcnt lgkmcnt(3)
	v_pk_mul_f32 v[70:71], v[70:71], v[134:135]
	v_pk_mul_f32 v[72:73], v[72:73], v[136:137]
	v_pk_mul_f32 v[74:75], v[74:75], v[196:197]
	v_pk_mul_f32 v[76:77], v[76:77], v[198:199]
	ds_read_b64_tr_b16 v[134:135], v159 offset:12288
	ds_read_b64_tr_b16 v[136:137], v158 offset:13312
	ds_read_b128 v[196:199], v183 offset:8192
	s_waitcnt lgkmcnt(3)
	v_mfma_f32_32x32x16_bf16 v[66:81], v[250:253], v[130:133], v[66:81]
	ds_read_b64_tr_b16 v[130:131], v159 offset:16384
	ds_read_b64_tr_b16 v[132:133], v158 offset:17408
	ds_read_b128 v[250:253], v182 offset:8192
	s_waitcnt lgkmcnt(3)
	v_mfma_f32_32x32x16_bf16 v[66:81], v[196:199], v[134:137], v[66:81]
	ds_read_b64_tr_b16 v[134:135], v159 offset:20480
	ds_read_b64_tr_b16 v[136:137], v158 offset:21504
	ds_read_b128 v[196:199], v184 offset:8192
	s_waitcnt lgkmcnt(3)
	v_mfma_f32_32x32x16_bf16 v[66:81], v[250:253], v[130:133], v[66:81]
	ds_read_b64_tr_b16 v[130:131], v159 offset:24576
	ds_read_b64_tr_b16 v[132:133], v158 offset:25600
	ds_read_b128 v[250:253], v185 offset:8192
	s_waitcnt lgkmcnt(3)
	v_mfma_f32_32x32x16_bf16 v[66:81], v[196:199], v[134:137], v[66:81]
	ds_read_b64_tr_b16 v[134:135], v159 offset:28672
	ds_read_b64_tr_b16 v[136:137], v158 offset:29696
	ds_read_b128 v[196:199], v186 offset:8192
	s_waitcnt lgkmcnt(3)
	v_mfma_f32_32x32x16_bf16 v[66:81], v[250:253], v[130:133], v[66:81]
	s_waitcnt lgkmcnt(0)
	v_mfma_f32_32x32x16_bf16 v[66:81], v[196:199], v[134:137], v[66:81]
.Lpv1_done:
	s_cbranch_vccnz .LBB0_524
	s_add_i32 s2, 0, 0x20a00
	v_add_u32_e32 v145, s2, v164
	ds_read_b128 v[130:133], v145 offset:224
	ds_read_b128 v[134:137], v145 offset:192
	ds_read_b128 v[196:199], v145 offset:160
	ds_read_b128 v[250:253], v145 offset:128
	s_waitcnt lgkmcnt(3)
	s_nop 3
	v_pk_mul_f32 v[78:79], v[78:79], v[130:131]
	s_waitcnt lgkmcnt(2)
	v_pk_mul_f32 v[74:75], v[74:75], v[134:135]
	s_waitcnt lgkmcnt(1)
	v_pk_mul_f32 v[70:71], v[70:71], v[196:197]
	v_pk_mul_f32 v[80:81], v[80:81], v[132:133]
	v_pk_mul_f32 v[76:77], v[76:77], v[136:137]
	v_pk_mul_f32 v[72:73], v[72:73], v[198:199]
	s_waitcnt lgkmcnt(0)
	v_pk_mul_f32 v[68:69], v[68:69], v[252:253]
	v_pk_mul_f32 v[66:67], v[66:67], v[250:251]

.LBB0_546:
	ds_read_b64 v[66:67], v165 offset:16384
	ds_read_b64 v[68:69], v166 offset:16384
	ds_read_b64 v[132:133], v167 offset:16384
	ds_read_b64 v[134:135], v168 offset:16384
	ds_read_b64 v[146:147], v169 offset:16384
	ds_read_b64 v[148:149], v170 offset:16384
	ds_read_b64 v[196:197], v171 offset:16384
	ds_read_b64 v[198:199], v172 offset:16384
	s_and_b64 vcc, exec, s[6:7]
	s_waitcnt lgkmcnt(6)
	v_mfma_f32_32x32x16_bf16 v[66:81], v[66:69], v[98:101], 0
	ds_read_b64 v[200:201], v173 offset:16384
	ds_read_b64 v[202:203], v174 offset:16384
	s_waitcnt lgkmcnt(6)
	v_mfma_f32_32x32x16_bf16 v[66:81], v[132:135], v[102:105], v[66:81]
	ds_read_b64 v[132:133], v175 offset:16384
	ds_read_b64 v[134:135], v176 offset:16384
	s_waitcnt lgkmcnt(6)
	v_mfma_f32_32x32x16_bf16 v[66:81], v[146:149], v[106:109], v[66:81]
	ds_read_b64 v[146:147], v178 offset:16384
	ds_read_b64 v[148:149], v179 offset:16384
	s_waitcnt lgkmcnt(6)
	v_mfma_f32_32x32x16_bf16 v[66:81], v[196:199], v[110:113], v[66:81]
	ds_read_b64 v[196:197], v180 offset:16384
	ds_read_b64 v[198:199], v181 offset:16384
	s_waitcnt lgkmcnt(6)
	v_mfma_f32_32x32x16_bf16 v[66:81], v[200:203], v[114:117], v[66:81]
	ds_read_b128 v[200:203], v219 offset:352
	s_waitcnt lgkmcnt(5)
	v_mfma_f32_32x32x16_bf16 v[66:81], v[132:135], v[118:121], v[66:81]
	ds_read_b128 v[132:135], v219 offset:256
	s_waitcnt lgkmcnt(4)
	v_mfma_f32_32x32x16_bf16 v[66:81], v[146:149], v[122:125], v[66:81]
	ds_read_b128 v[146:149], v219 offset:288
	s_waitcnt lgkmcnt(3)
	v_mfma_f32_32x32x16_bf16 v[66:81], v[196:199], v[126:129], v[66:81]
	ds_read_b128 v[196:199], v219 offset:320
	s_waitcnt lgkmcnt(2)
	s_nop 9
	s_cmp_lg_u32 s4, 0
	s_cbranch_scc0 .Lpv2_bwd
	v_pk_mul_f32 v[78:79], v[78:79], v[200:201]
	v_pk_mul_f32 v[80:81], v[80:81], v[202:203]
	v_pk_mul_f32 v[66:67], v[66:67], v[132:133]
	v_pk_mul_f32 v[68:69], v[68:69], v[134:135]
	ds_read_b64_tr_b16 v[132:133], v159
	ds_read_b64_tr_b16 v[134:135], v158 offset:1024
	ds_read_b128 v[200:203], v187
	s_waitcnt lgkmcnt(3)
	v_pk_mul_f32 v[70:71], v[70:71], v[146:147]
	v_pk_mul_f32 v[72:73], v[72:73], v[148:149]
	v_pk_mul_f32 v[74:75], v[74:75], v[196:197]
	v_pk_mul_f32 v[76:77], v[76:77], v[198:199]
	ds_read_b64_tr_b16 v[146:147], v159 offset:4096
	ds_read_b64_tr_b16 v[148:149], v158 offset:5120
	ds_read_b128 v[196:199], v188
	s_waitcnt lgkmcnt(3)
	v_mfma_f32_32x32x16_bf16 v[66:81], v[200:203], v[132:135], v[66:81]
	ds_read_b64_tr_b16 v[132:133], v159 offset:8192
	ds_read_b64_tr_b16 v[134:135], v158 offset:9216
	ds_read_b128 v[200:203], v189
	s_waitcnt lgkmcnt(3)
	v_mfma_f32_32x32x16_bf16 v[66:81], v[196:199], v[146:149], v[66:81]
	ds_read_b64_tr_b16 v[146:147], v159 offset:12288
	ds_read_b64_tr_b16 v[148:149], v158 offset:13312
	ds_read_b128 v[196:199], v183
	s_waitcnt lgkmcnt(3)
	v_mfma_f32_32x32x16_bf16 v[66:81], v[200:203], v[132:135], v[66:81]
	ds_read_b64_tr_b16 v[132:133], v159 offset:16384
	ds_read_b64_tr_b16 v[134:135], v158 offset:17408
	ds_read_b128 v[200:203], v182
	s_waitcnt lgkmcnt(3)
	v_mfma_f32_32x32x16_bf16 v[66:81], v[196:199], v[146:149], v[66:81]
	ds_read_b64_tr_b16 v[146:147], v159 offset:20480
	ds_read_b64_tr_b16 v[148:149], v158 offset:21504
	ds_read_b128 v[196:199], v184
	s_waitcnt lgkmcnt(3)
	v_mfma_f32_32x32x16_bf16 v[66:81], v[200:203], v[132:135], v[66:81]
	s_waitcnt lgkmcnt(0)
	v_mfma_f32_32x32x16_bf16 v[66:81], v[196:199], v[146:149], v[66:81]
	s_branch .Lpv2_done
.Lpv2_bwd:
	v_pk_mul_f32 v[78:79], v[78:79], v[200:201]
	v_pk_mul_f32 v[80:81], v[80:81], v[202:203]
	v_pk_mul_f32 v[66:67], v[66:67], v[132:133]
	v_pk_mul_f32 v[68:69], v[68:69], v[134:135]
	ds_read_b64_tr_b16 v[132:133], v159 offset:16384
	ds_read_b64_tr_b16 v[134:135], v158 offset:17408
	ds_read_b128 v[200:203], v182
	s_waitcnt lgkmcnt(3)
	v_pk_mul_f32 v[70:71], v[70:71], v[146:147]
	v_pk_mul_f32 v[72:73], v[72:73], v[148:149]
	v_pk_mul_f32 v[74:75], v[74:75], v[196:197]
	v_pk_mul_f32 v[76:77], v[76:77], v[198:199]
	ds_read_b64_tr_b16 v[146:147], v159 offset:20480
	ds_read_b64_tr_b16 v[148:149], v158 offset:21504
	ds_read_b128 v[196:199], v184
	s_waitcnt lgkmcnt(3)
	v_mfma_f32_32x32x16_bf16 v[66:81], v[200:203], v[132:135], v[66:81]
	ds_read_b64_tr_b16 v[132:133], v159 offset:24576
	ds_read_b64_tr_b16 v[134:135], v158 offset:25600
	ds_read_b128 v[200:203], v185
	s_waitcnt lgkmcnt(3)
	v_mfma_f32_32x32x16_bf16 v[66:81], v[196:199], v[146:149], v[66:81]
	ds_read_b64_tr_b16 v[146:147], v159 offset:28672
	ds_read_b64_tr_b16 v[148:149], v158 offset:29696
	ds_read_b128 v[196:199], v186
	s_waitcnt lgkmcnt(3)
	v_mfma_f32_32x32x16_bf16 v[66:81], v[200:203], v[132:135], v[66:81]
	s_waitcnt lgkmcnt(0)
	v_mfma_f32_32x32x16_bf16 v[66:81], v[196:199], v[146:149], v[66:81]
.Lpv2_done:
	s_cbranch_vccz .LBB0_560
	s_and_b64 vcc, exec, s[14:15]
	s_mov_b64 s[10:11], -1
	s_cbranch_vccz .LBB0_561

.LBB0_550:
	s_nop 5
	ds_read_b64 v[66:67], v165 offset:24576
	ds_read_b64 v[68:69], v166 offset:24576
	s_and_b64 vcc, exec, s[6:7]
	s_waitcnt lgkmcnt(0)
	v_mfma_f32_32x32x16_bf16 v[66:81], v[66:69], v[98:101], 0
	ds_read_b64 v[98:99], v167 offset:24576
	ds_read_b64 v[100:101], v168 offset:24576
	s_waitcnt lgkmcnt(0)
	v_mfma_f32_32x32x16_bf16 v[66:81], v[98:101], v[102:105], v[66:81]
	ds_read_b64 v[98:99], v169 offset:24576
	ds_read_b64 v[100:101], v170 offset:24576
	s_waitcnt lgkmcnt(0)
	v_mfma_f32_32x32x16_bf16 v[66:81], v[98:101], v[106:109], v[66:81]
	ds_read_b64 v[98:99], v171 offset:24576
	ds_read_b64 v[100:101], v172 offset:24576
	s_waitcnt lgkmcnt(0)
	v_mfma_f32_32x32x16_bf16 v[66:81], v[98:101], v[110:113], v[66:81]
	ds_read_b64 v[98:99], v173 offset:24576
	ds_read_b64 v[100:101], v174 offset:24576
	s_waitcnt lgkmcnt(0)
	v_mfma_f32_32x32x16_bf16 v[66:81], v[98:101], v[114:117], v[66:81]
	ds_read_b64 v[98:99], v175 offset:24576
	ds_read_b64 v[100:101], v176 offset:24576
	s_waitcnt lgkmcnt(0)
	v_mfma_f32_32x32x16_bf16 v[66:81], v[98:101], v[118:121], v[66:81]
	ds_read_b64 v[98:99], v178 offset:24576
	ds_read_b64 v[100:101], v179 offset:24576
	s_waitcnt lgkmcnt(0)
	v_mfma_f32_32x32x16_bf16 v[66:81], v[98:101], v[122:125], v[66:81]
	ds_read_b64 v[98:99], v180 offset:24576
	ds_read_b64 v[100:101], v181 offset:24576
	s_waitcnt lgkmcnt(0)
	v_mfma_f32_32x32x16_bf16 v[66:81], v[98:101], v[126:129], v[66:81]
	ds_read_b128 v[98:101], v219 offset:384
	ds_read_b128 v[102:105], v219 offset:416
	ds_read_b128 v[106:109], v219 offset:448
	ds_read_b128 v[110:113], v219 offset:480
	s_waitcnt lgkmcnt(2)
	s_nop 6
	v_pk_mul_f32 v[72:73], v[72:73], v[104:105]
	v_pk_mul_f32 v[70:71], v[70:71], v[102:103]
	v_pk_mul_f32 v[68:69], v[68:69], v[100:101]
	v_pk_mul_f32 v[66:67], v[66:67], v[98:99]
	s_cmp_lg_u32 s4, 0
	s_cbranch_scc0 .Lpv3_bwd
	ds_read_b64_tr_b16 v[98:99], v159
	ds_read_b64_tr_b16 v[100:101], v158 offset:1024
	ds_read_b128 v[102:105], v187 offset:8192
	s_waitcnt lgkmcnt(3)
	v_pk_mul_f32 v[80:81], v[80:81], v[112:113]
	v_pk_mul_f32 v[78:79], v[78:79], v[110:111]
	v_pk_mul_f32 v[76:77], v[76:77], v[108:109]
	v_pk_mul_f32 v[74:75], v[74:75], v[106:107]
	s_waitcnt lgkmcnt(0)
	s_nop 0
	v_mfma_f32_32x32x16_bf16 v[66:81], v[102:105], v[98:101], v[66:81]
	ds_read_b64_tr_b16 v[98:99], v159 offset:4096
	ds_read_b64_tr_b16 v[100:101], v158 offset:5120
	ds_read_b128 v[102:105], v188 offset:8192
	s_waitcnt lgkmcnt(0)
	v_mfma_f32_32x32x16_bf16 v[66:81], v[102:105], v[98:101], v[66:81]
	ds_read_b64_tr_b16 v[98:99], v159 offset:8192
	ds_read_b64_tr_b16 v[100:101], v158 offset:9216
	ds_read_b128 v[102:105], v189 offset:8192
	s_waitcnt lgkmcnt(0)
	v_mfma_f32_32x32x16_bf16 v[66:81], v[102:105], v[98:101], v[66:81]
	ds_read_b64_tr_b16 v[98:99], v159 offset:12288
	ds_read_b64_tr_b16 v[100:101], v158 offset:13312
	ds_read_b128 v[102:105], v183 offset:8192
	s_waitcnt lgkmcnt(0)
	v_mfma_f32_32x32x16_bf16 v[66:81], v[102:105], v[98:101], v[66:81]
	ds_read_b64_tr_b16 v[98:99], v159 offset:16384
	ds_read_b64_tr_b16 v[100:101], v158 offset:17408
	ds_read_b128 v[102:105], v182 offset:8192
	s_waitcnt lgkmcnt(0)
	v_mfma_f32_32x32x16_bf16 v[66:81], v[102:105], v[98:101], v[66:81]
	ds_read_b64_tr_b16 v[98:99], v159 offset:20480
	ds_read_b64_tr_b16 v[100:101], v158 offset:21504
	ds_read_b128 v[102:105], v184 offset:8192
	s_waitcnt lgkmcnt(0)
	v_mfma_f32_32x32x16_bf16 v[66:81], v[102:105], v[98:101], v[66:81]
	ds_read_b64_tr_b16 v[98:99], v159 offset:24576
	ds_read_b64_tr_b16 v[100:101], v158 offset:25600
	ds_read_b128 v[102:105], v185 offset:8192
	s_branch .Lpv3_tail
.Lpv3_bwd:
	ds_read_b64_tr_b16 v[98:99], v159 offset:24576
	ds_read_b64_tr_b16 v[100:101], v158 offset:25600
	ds_read_b128 v[102:105], v185 offset:8192
	s_waitcnt lgkmcnt(3)
	v_pk_mul_f32 v[80:81], v[80:81], v[112:113]
	v_pk_mul_f32 v[78:79], v[78:79], v[110:111]
	v_pk_mul_f32 v[76:77], v[76:77], v[108:109]
	v_pk_mul_f32 v[74:75], v[74:75], v[106:107]
.Lpv3_tail:
	s_waitcnt lgkmcnt(0)
	s_nop 0
	v_mfma_f32_32x32x16_bf16 v[66:81], v[102:105], v[98:101], v[66:81]
	ds_read_b64_tr_b16 v[98:99], v159 offset:28672
	ds_read_b64_tr_b16 v[100:101], v158 offset:29696
	ds_read_b128 v[102:105], v186 offset:8192
	s_waitcnt lgkmcnt(0)
	v_mfma_f32_32x32x16_bf16 v[66:81], v[102:105], v[98:101], v[66:81]
	s_cbranch_vccz .LBB0_570
	s_and_b64 vcc, exec, s[14:15]
	s_mov_b64 s[10:11], -1
	s_cbranch_vccz .LBB0_571
